# stack9 + attention phase entry: the six kernarg pointer fetches (four serialised load-wait-use round trips + two behind the lambda reduction) issued together into dead SGPRs, one wait
# speedup vs baseline: 1.0011x; 1.0011x over previous
.LBB0_306:
	s_load_dwordx2 s[20:21], s[58:59], 0x38
	s_load_dwordx2 s[22:23], s[58:59], 0x40
	s_load_dwordx2 s[24:25], s[58:59], 0x48
	s_load_dwordx2 s[26:27], s[58:59], 0x50
	s_load_dwordx2 s[28:29], s[58:59], 0xa0
	s_load_dwordx2 s[30:31], s[58:59], 0x58
	v_mbcnt_lo_u32_b32 v0, -1, s1
	s_movk_i32 s1, 0xa0
	s_mov_b32 s2, 56
	v_mbcnt_hi_u32_b32 v0, -1, v0
	s_waitcnt vmcnt(0)
	v_lshl_add_u32 v2, s60, 6, v0
	s_waitcnt lgkmcnt(0)
	v_ashrrev_i32_e32 v3, 31, v2
	v_lshlrev_b64 v[2:3], 2, v[2:3]
	s_waitcnt lgkmcnt(0)
	v_lshl_add_u64 v[4:5], s[20:21], 0, v[2:3]
	s_mov_b32 s2, 64
	global_load_dword v6, v[4:5], off
	s_movk_i32 s4, 0x50
	s_cmpk_gt_i32 s55, 0xff
	s_waitcnt lgkmcnt(0)
	v_lshl_add_u64 v[4:5], s[22:23], 0, v[2:3]
	s_movk_i32 s2, 0x48
	global_load_dword v7, v[4:5], off
	s_waitcnt lgkmcnt(0)
	v_lshl_add_u64 v[4:5], s[24:25], 0, v[2:3]
	global_load_dword v4, v[4:5], off
	v_lshlrev_b32_e32 v5, 2, v0
	v_xor_b32_e32 v8, 4, v5
	s_waitcnt lgkmcnt(0)
	v_lshl_add_u64 v[2:3], s[26:27], 0, v[2:3]
	global_load_dword v2, v[2:3], off
	s_movk_i32 s2, 0x58
	s_waitcnt vmcnt(0)
	v_mul_f32_e32 v3, v6, v7
	ds_bpermute_b32 v3, v8, v3
	s_waitcnt lgkmcnt(0)
	v_fmac_f32_e32 v3, v6, v7
	v_xor_b32_e32 v6, 8, v5
	ds_bpermute_b32 v7, v6, v3
	s_waitcnt lgkmcnt(0)
	v_add_f32_e32 v3, v3, v7
	v_xor_b32_e32 v7, 16, v5
	v_mul_f32_e32 v9, v4, v2
	ds_bpermute_b32 v8, v8, v9
	ds_bpermute_b32 v9, v7, v3
	s_waitcnt lgkmcnt(1)
	v_fmac_f32_e32 v8, v4, v2
	ds_bpermute_b32 v2, v6, v8
	s_waitcnt lgkmcnt(1)
	v_add_f32_e32 v3, v3, v9
	v_xor_b32_e32 v6, 32, v5
	s_waitcnt lgkmcnt(0)
	v_add_f32_e32 v2, v8, v2
	ds_bpermute_b32 v4, v7, v2
	ds_bpermute_b32 v7, v6, v3
	s_waitcnt lgkmcnt(1)
	v_add_f32_e32 v2, v2, v4
	ds_bpermute_b32 v4, v6, v2
	s_waitcnt lgkmcnt(1)
	v_add_f32_e32 v3, v3, v7
	v_xor_b32_e32 v6, 64, v5
	ds_bpermute_b32 v7, v6, v3
	v_xor_b32_e32 v5, 0x80, v5
	s_waitcnt lgkmcnt(1)
	v_add_f32_e32 v4, v2, v4
	ds_bpermute_b32 v6, v6, v4
	s_waitcnt lgkmcnt(1)
	v_add_f32_e32 v2, v3, v7
	ds_bpermute_b32 v3, v5, v2
	s_waitcnt lgkmcnt(1)
	v_add_f32_e32 v4, v4, v6
	ds_bpermute_b32 v5, v5, v4
	s_cbranch_scc1 .LBB0_494
	s_mov_b64 s[4:5], s[28:29]
	v_mov_b32_e32 v6, 0x3eb60549
	s_mov_b64 s[2:3], s[30:31]
	v_mov_b32_e32 v7, 0x3e4ccccd
	v_cndmask_b32_e64 v6, v6, v7, s[6:7]
	s_waitcnt lgkmcnt(0)
	s_add_u32 s56, s4, 0xa100000
	s_addc_u32 s57, s5, 0
	s_add_u32 s58, s4, 0x12100000
	s_addc_u32 s59, s5, 0
	s_mov_b32 s6, s60
	s_add_u32 s60, s4, 0x14100000
	s_addc_u32 s61, s5, 0
	s_add_u32 s62, s4, 0x16100000
	s_addc_u32 s63, s5, 0
	s_lshl_b32 s88, s6, 7
	v_add_f32_e32 v2, v2, v3
	s_mov_b32 s90, s6
	s_lshl_b64 s[6:7], s[88:89], 2
	v_add_f32_e32 v3, v4, v5
	s_add_u32 s20, s2, s6
	v_mul_f32_e32 v4, 0x3fb8aa3b, v2
	s_mov_b32 s2, 0x3fb8aa3b
	v_fma_f32 v5, v2, s2, -v4
	v_rndne_f32_e32 v7, v4
	v_fmac_f32_e32 v5, 0x32a5705f, v2
	v_sub_f32_e32 v4, v4, v7
	v_add_f32_e32 v4, v4, v5
	v_exp_f32_e32 v4, v4
	v_cvt_i32_f32_e32 v5, v7
	s_addc_u32 s21, s3, s7
	s_ashr_i32 s1, s0, 31
	s_lshl_b64 s[0:1], s[0:1], 16
	v_ldexp_f32 v4, v4, v5
	v_mul_f32_e32 v5, 0x3fb8aa3b, v3
	v_fma_f32 v7, v3, s2, -v5
	v_rndne_f32_e32 v8, v5
	v_fmac_f32_e32 v7, 0x32a5705f, v3
	v_sub_f32_e32 v5, v5, v8
	s_add_u32 s0, s4, s0
	v_add_f32_e32 v5, v5, v7
	s_addc_u32 s1, s5, s1
	v_exp_f32_e32 v5, v5
	v_cvt_i32_f32_e32 v7, v8
	s_add_u32 s64, s0, 0x1c100000
	s_mov_b32 s0, 0xc2ce8ed0
	s_addc_u32 s65, s1, 0
	v_cmp_ngt_f32_e32 vcc, s0, v2
	s_mov_b32 s1, 0x42b17218
	v_mov_b32_e32 v8, 0x7f800000
	v_cndmask_b32_e32 v4, 0, v4, vcc
	v_cmp_nlt_f32_e32 vcc, s1, v2
	v_add_u32_e32 v222, s51, v0
	v_and_b32_e32 v223, 63, v0
	v_cndmask_b32_e32 v2, v8, v4, vcc
	v_ldexp_f32 v4, v5, v7
	v_cmp_ngt_f32_e32 vcc, s0, v3
	v_bfe_u32 v225, v0, 2, 4
	v_sub_f32_e32 v221, 1.0, v6
	v_cndmask_b32_e32 v4, 0, v4, vcc
	v_cmp_nlt_f32_e32 vcc, s1, v3
	v_lshlrev_b32_e32 v224, 10, v223
	v_lshlrev_b32_e32 v235, 4, v223
	v_cndmask_b32_e32 v3, v8, v4, vcc
	v_sub_f32_e32 v2, v2, v3
	v_add_f32_e32 v220, v6, v2
	v_bfe_u32 v2, v0, 5, 1
	v_lshlrev_b32_e32 v3, 3, v0
	v_lshlrev_b32_e32 v4, 4, v222
	v_lshlrev_b32_e32 v0, 1, v0
	v_and_b32_e32 v232, 24, v3
	v_lshlrev_b32_e32 v3, 10, v2
	v_and_b32_e32 v5, 0x1f0, v4
	v_and_b32_e32 v0, 32, v0
	v_add3_u32 v233, 0, v3, v5
	v_add3_u32 v0, 0, v0, v232
	v_lshlrev_b32_e32 v2, 8, v2
	v_and_b32_e32 v3, 0xc0, v4
	v_add3_u32 v234, v0, v2, v3
	s_mov_b32 s66, s55
	s_branch .LBB0_309
